# step 0 RMSNorm: each row's 12 ln/shift/scale vector loads issued together (row 0's ahead of the next-rows prefetch) with counted waits instead of 13 serialized vmcnt(0) round trips per iteration
# baseline (speedup 1.0000x reference)
; __device__ __forceinline__ void phase_norm(const float* src32, const h16* src16, const float* ln, const float* modl, int shi, int sci, h16* dst) {
;     ...
;                 const int b = row >> 12;
;                 const float* sh = modl + b * 9216 + shi * 1024; const float* sc = modl + b * 9216 + sci * 1024;
; #pragma unroll
;                 for (int i = 0; i < 4; ++i) {
;                     const int col = src32 ? (4 * lane + 256 * i) : (16 * lane + 4 * i);
;                     const f32x4 gv = *(const f32x4*)(ln + col), sv = *(const f32x4*)(sh + col), cv = *(const f32x4*)(sc + col);
.LBB0_776:
	s_ashr_i32 s64, s8, 12
	s_mulk_i32 s64, 0x2400
	s_ashr_i32 s65, s64, 31
	s_lshl_b64 s[64:65], s[64:65], 2
	v_readlane_b32 s66, v255, 13
	v_readlane_b32 s67, v255, 15
	s_nop 1
	s_add_u32 s60, s66, s64
	s_addc_u32 s61, s67, s65
	s_add_u32 s62, s60, 0x1000
	s_addc_u32 s63, s61, 0
	global_load_dwordx4 v[204:207], v[72:73], off
	v_lshlrev_b32_e32 v176, 2, v70
	v_mov_b32_e32 v177, v33
	v_lshl_add_u64 v[178:179], s[60:61], 0, v[176:177]
	global_load_dwordx4 v[208:211], v[178:179], off
	v_lshl_add_u64 v[180:181], s[62:63], 0, v[176:177]
	global_load_dwordx4 v[212:215], v[180:181], off
	global_load_dwordx4 v[216:219], v[76:77], off
	v_lshlrev_b32_e32 v176, 2, v74
	v_mov_b32_e32 v177, v33
	v_lshl_add_u64 v[178:179], s[60:61], 0, v[176:177]
	global_load_dwordx4 v[220:223], v[178:179], off
	v_lshl_add_u64 v[180:181], s[62:63], 0, v[176:177]
	global_load_dwordx4 v[224:227], v[180:181], off
	global_load_dwordx4 v[228:231], v[80:81], off
	v_lshlrev_b32_e32 v176, 2, v78
	v_mov_b32_e32 v177, v33
	v_lshl_add_u64 v[178:179], s[60:61], 0, v[176:177]
	global_load_dwordx4 v[232:235], v[178:179], off
	v_lshl_add_u64 v[180:181], s[62:63], 0, v[176:177]
	global_load_dwordx4 v[236:239], v[180:181], off
	global_load_dwordx4 v[240:243], v[84:85], off
	v_lshlrev_b32_e32 v176, 2, v82
	v_mov_b32_e32 v177, v33
	v_lshl_add_u64 v[178:179], s[60:61], 0, v[176:177]
	global_load_dwordx4 v[244:247], v[178:179], off
	v_lshl_add_u64 v[180:181], s[62:63], 0, v[176:177]
	global_load_dwordx4 v[248:251], v[180:181], off
	s_add_i32 s16, s8, s17
	s_cmpk_gt_i32 s16, 0x7fff
	s_cselect_b64 s[0:1], -1, 0
	s_and_b64 vcc, exec, s[0:1]
	s_cbranch_vccnz .LBB0_786
	s_add_i32 s20, s14, s3
	s_and_b64 vcc, exec, s[4:5]
	s_mov_b64 s[6:7], -1
	s_cbranch_vccz .LBB0_780
	s_andn2_b64 vcc, exec, s[6:7]
	s_cbranch_vccz .LBB0_781

; __device__ __forceinline__ void phase_norm(const float* src32, const h16* src16, const float* ln, const float* modl, int shi, int sci, h16* dst) {
;     ...
;             if (row < M_TOK) {
;                 float ss = 0.f;
; #pragma unroll
;                 for (int i = 0; i < 4; ++i) ss += vc[u][i][0] * vc[u][i][0] + vc[u][i][1] * vc[u][i][1] + vc[u][i][2] * vc[u][i][2] + vc[u][i][3] * vc[u][i][3];
;                 ss = wave_sum(ss, lane);
;                 const float rstd = rsqrtf(ss * (1.0f / 1024.0f) + 1e-6f);
;                 const int b = row >> 12;
;                 const float* sh = modl + b * 9216 + shi * 1024; const float* sc = modl + b * 9216 + sci * 1024;
; #pragma unroll
;                 for (int i = 0; i < 4; ++i) {
;                     const int col = src32 ? (4 * lane + 256 * i) : (16 * lane + 4 * i);
;                     const f32x4 gv = *(const f32x4*)(ln + col), sv = *(const f32x4*)(sh + col), cv = *(const f32x4*)(sc + col);
;                     h16x4 o;
; #pragma unroll
;                     for (int j = 0; j < 4; ++j) o[j] = (h16)(vc[u][i][j] * rstd * gv[j] * (1.0f + cv[j]) + sv[j]);
;                     gst((h16x4*)(dst + (unsigned)row * DM + col), o);
;                 }
.LBB0_786:
	s_waitcnt vmcnt(12)
	v_mov_b32_e32 v92, v59
	v_mov_b32_e32 v93, v63
	v_mov_b32_e32 v90, v58
	v_mov_b32_e32 v91, v62
	v_pk_mul_f32 v[92:93], v[92:93], v[92:93]
	v_mov_b32_e32 v94, v29
	v_pk_fma_f32 v[90:91], v[90:91], v[90:91], v[92:93]
	v_mov_b32_e32 v92, v60
	v_mov_b32_e32 v93, v64
	v_pk_fma_f32 v[90:91], v[92:93], v[92:93], v[90:91]
	v_mov_b32_e32 v92, v61
	v_mov_b32_e32 v93, v65
	v_mov_b32_e32 v95, v55
	v_pk_fma_f32 v[90:91], v[92:93], v[92:93], v[90:91]
	v_mov_b32_e32 v92, v28
	v_mov_b32_e32 v93, v54
	v_pk_mul_f32 v[94:95], v[94:95], v[94:95]
	v_add_f32_e32 v32, v90, v91
	v_pk_fma_f32 v[92:93], v[92:93], v[92:93], v[94:95]
	v_mov_b32_e32 v94, v30
	v_mov_b32_e32 v95, v56
	v_pk_fma_f32 v[92:93], v[94:95], v[94:95], v[92:93]
	v_mov_b32_e32 v94, v31
	v_mov_b32_e32 v95, v57
	v_pk_fma_f32 v[92:93], v[94:95], v[94:95], v[92:93]
	s_mov_b32 s6, 0x800000
	v_add_f32_e32 v32, v93, v32
	v_add_f32_e32 v32, v92, v32
	ds_bpermute_b32 v86, v71, v32
	s_waitcnt lgkmcnt(0)
	v_add_f32_e32 v32, v32, v86
	ds_bpermute_b32 v86, v75, v32
	s_waitcnt lgkmcnt(0)
	v_add_f32_e32 v32, v32, v86
	ds_bpermute_b32 v86, v79, v32
	s_waitcnt lgkmcnt(0)
	v_add_f32_e32 v32, v32, v86
	ds_bpermute_b32 v86, v83, v32
	s_waitcnt lgkmcnt(0)
	v_add_f32_e32 v32, v32, v86
	ds_bpermute_b32 v86, v87, v32
	s_waitcnt lgkmcnt(0)
	v_add_f32_e32 v32, v32, v86
	ds_bpermute_b32 v86, v88, v32
	s_waitcnt lgkmcnt(0)
	v_add_f32_e32 v32, v32, v86
	v_fmamk_f32 v32, v32, 0x3a800000, v193
	v_cmp_gt_f32_e32 vcc, s6, v32
	v_mul_f32_e32 v86, 0x4b800000, v32
	s_ashr_i32 s6, s8, 12
	v_cndmask_b32_e32 v32, v32, v86, vcc
	s_mulk_i32 s6, 0x2400
	v_rsq_f32_e32 v32, v32
	s_ashr_i32 s7, s6, 31
	s_lshl_b64 s[6:7], s[6:7], 2
	v_readlane_b32 s8, v255, 13
	s_add_u32 s10, s8, s6
	v_readlane_b32 s6, v255, 15
	s_addc_u32 s11, s6, s7
	v_mul_f32_e32 v86, 0x45800000, v32
	s_add_u32 s8, s10, 0x1000
	v_cndmask_b32_e32 v86, v32, v86, vcc
	s_addc_u32 s9, s11, 0
	v_lshlrev_b32_e32 v32, 2, v70
	v_lshl_add_u64 v[94:95], s[10:11], 0, v[32:33]
	v_lshl_add_u64 v[98:99], s[8:9], 0, v[32:33]
	v_pk_mul_f32 v[62:63], v[62:63], v[86:87] op_sel_hi:[1,0]
	s_add_i32 s20, s2, s3
	v_pk_mul_f32 v[64:65], v[64:65], v[86:87] op_sel_hi:[1,0]
	s_lshl_b64 s[6:7], s[20:21], 1
	s_add_u32 s6, s84, s6
	s_addc_u32 s7, s85, s7
	v_pk_mul_f32 v[58:59], v[58:59], v[86:87] op_sel_hi:[1,0]
	v_pk_mul_f32 v[60:61], v[60:61], v[86:87] op_sel_hi:[1,0]
	v_pk_mul_f32 v[54:55], v[54:55], v[86:87] op_sel_hi:[1,0]
	v_pk_mul_f32 v[56:57], v[56:57], v[86:87] op_sel_hi:[1,0]
	v_pk_mul_f32 v[28:29], v[28:29], v[86:87] op_sel_hi:[1,0]
	s_cmpk_gt_i32 s12, 0x7fff
	s_waitcnt vmcnt(9)
	v_mov_b64_e32 v[90:91], v[204:205]
	v_mov_b64_e32 v[92:93], v[206:207]
	v_mov_b64_e32 v[94:95], v[208:209]
	v_mov_b64_e32 v[96:97], v[210:211]
	v_mov_b64_e32 v[98:99], v[212:213]
	v_mov_b64_e32 v[100:101], v[214:215]
	v_pk_mul_f32 v[62:63], v[90:91], v[62:63]
	v_pk_mul_f32 v[64:65], v[92:93], v[64:65]
	s_waitcnt lgkmcnt(0)
	v_pk_add_f32 v[90:91], v[98:99], 1.0 op_sel_hi:[1,0]
	s_nop 0
	v_pk_fma_f32 v[62:63], v[90:91], v[62:63], v[94:95]
	v_pk_add_f32 v[90:91], v[100:101], 1.0 op_sel_hi:[1,0]
	v_cvt_pk_f16_f32 v62, v62, v63
	v_pk_fma_f32 v[64:65], v[90:91], v[64:65], v[96:97]
	s_nop 0
	v_cvt_pk_f16_f32 v63, v64, v65
	v_lshlrev_b32_e32 v64, 1, v70
	global_store_dwordx2 v64, v[62:63], s[6:7]
	v_lshlrev_b32_e32 v62, 2, v74
	v_mov_b32_e32 v63, v33
	v_lshl_add_u64 v[94:95], s[10:11], 0, v[62:63]
	v_lshl_add_u64 v[98:99], s[8:9], 0, v[62:63]
	s_waitcnt vmcnt(9)
	v_mov_b64_e32 v[90:91], v[216:217]
	v_mov_b64_e32 v[92:93], v[218:219]
	v_pk_mul_f32 v[58:59], v[90:91], v[58:59]
	v_pk_mul_f32 v[60:61], v[92:93], v[60:61]
	s_waitcnt vmcnt(7) lgkmcnt(0)
	v_mov_b64_e32 v[94:95], v[220:221]
	v_mov_b64_e32 v[96:97], v[222:223]
	v_mov_b64_e32 v[98:99], v[224:225]
	v_mov_b64_e32 v[100:101], v[226:227]
	v_pk_add_f32 v[90:91], v[98:99], 1.0 op_sel_hi:[1,0]
	s_nop 0
	v_pk_fma_f32 v[58:59], v[90:91], v[58:59], v[94:95]
	v_pk_add_f32 v[90:91], v[100:101], 1.0 op_sel_hi:[1,0]
	v_cvt_pk_f16_f32 v58, v58, v59
	v_pk_fma_f32 v[60:61], v[90:91], v[60:61], v[96:97]
	s_nop 0
	v_cvt_pk_f16_f32 v59, v60, v61
	v_lshlrev_b32_e32 v60, 1, v74
	global_store_dwordx2 v60, v[58:59], s[6:7]
	v_lshlrev_b32_e32 v58, 2, v78
	v_mov_b32_e32 v59, v33
	v_lshl_add_u64 v[94:95], s[10:11], 0, v[58:59]
	v_lshl_add_u64 v[98:99], s[8:9], 0, v[58:59]
	s_waitcnt vmcnt(7)
	v_mov_b64_e32 v[90:91], v[228:229]
	v_mov_b64_e32 v[92:93], v[230:231]
	v_pk_mul_f32 v[54:55], v[90:91], v[54:55]
	v_pk_mul_f32 v[56:57], v[92:93], v[56:57]
	s_waitcnt vmcnt(5) lgkmcnt(0)
	v_mov_b64_e32 v[94:95], v[232:233]
	v_mov_b64_e32 v[96:97], v[234:235]
	v_mov_b64_e32 v[98:99], v[236:237]
	v_mov_b64_e32 v[100:101], v[238:239]
	v_pk_add_f32 v[90:91], v[98:99], 1.0 op_sel_hi:[1,0]
	s_nop 0
	v_pk_fma_f32 v[54:55], v[54:55], v[90:91], v[94:95]
	v_pk_add_f32 v[90:91], v[100:101], 1.0 op_sel_hi:[1,0]
	v_cvt_pk_f16_f32 v54, v54, v55
	v_pk_fma_f32 v[56:57], v[56:57], v[90:91], v[96:97]
	s_nop 0
	v_cvt_pk_f16_f32 v55, v56, v57
	v_lshlrev_b32_e32 v56, 1, v78
	global_store_dwordx2 v56, v[54:55], s[6:7]
	v_lshlrev_b32_e32 v54, 2, v82
	v_mov_b32_e32 v55, v33
	v_lshl_add_u64 v[94:95], s[10:11], 0, v[54:55]
	v_lshl_add_u64 v[98:99], s[8:9], 0, v[54:55]
	s_waitcnt vmcnt(5)
	v_mov_b64_e32 v[90:91], v[240:241]
	v_mov_b64_e32 v[92:93], v[242:243]
	v_pk_mul_f32 v[28:29], v[28:29], v[90:91]
	s_nop 0
	s_waitcnt vmcnt(3) lgkmcnt(0)
	v_mov_b64_e32 v[94:95], v[244:245]
	v_mov_b64_e32 v[96:97], v[246:247]
	v_mov_b64_e32 v[98:99], v[248:249]
	v_mov_b64_e32 v[100:101], v[250:251]
	v_pk_add_f32 v[90:91], v[98:99], 1.0 op_sel_hi:[1,0]
	s_nop 0
	v_pk_fma_f32 v[28:29], v[28:29], v[90:91], v[94:95]
	s_nop 0
	v_cvt_pk_f16_f32 v90, v28, v29
	v_pk_mul_f32 v[28:29], v[30:31], v[86:87] op_sel_hi:[1,0]
	v_pk_add_f32 v[30:31], v[100:101], 1.0 op_sel_hi:[1,0]
	v_pk_mul_f32 v[28:29], v[28:29], v[92:93]
	s_nop 0
	v_pk_fma_f32 v[28:29], v[28:29], v[30:31], v[96:97]
	s_nop 0
	v_cvt_pk_f16_f32 v91, v28, v29
	v_lshlrev_b32_e32 v28, 1, v82
	global_store_dwordx2 v28, v[90:91], s[6:7]
	s_cbranch_scc1 .LBB0_775
; __device__ __forceinline__ void phase_norm(const float* src32, const h16* src16, const float* ln, const float* modl, int shi, int sci, h16* dst) {
;     ...
;         for (int u = 0; u < 2; ++u) {
;             const int row = row0 + u * half;
;             if (row < M_TOK) {
;                 float ss = 0.f;
; #pragma unroll
;                 for (int i = 0; i < 4; ++i) ss += vc[u][i][0] * vc[u][i][0] + vc[u][i][1] * vc[u][i][1] + vc[u][i][2] * vc[u][i][2] + vc[u][i][3] * vc[u][i][3];
;                 ss = wave_sum(ss, lane);
;                 const float rstd = rsqrtf(ss * (1.0f / 1024.0f) + 1e-6f);
;                 const int b = row >> 12;
;                 const float* sh = modl + b * 9216 + shi * 1024; const float* sc = modl + b * 9216 + sci * 1024;
; #pragma unroll
;                 for (int i = 0; i < 4; ++i) {
;                     const int col = src32 ? (4 * lane + 256 * i) : (16 * lane + 4 * i);
;                     const f32x4 gv = *(const f32x4*)(ln + col), sv = *(const f32x4*)(sh + col), cv = *(const f32x4*)(sc + col);
;                     h16x4 o;
; #pragma unroll
;                     for (int j = 0; j < 4; ++j) o[j] = (h16)(vc[u][i][j] * rstd * gv[j] * (1.0f + cv[j]) + sv[j]);
;                     gst((h16x4*)(dst + (unsigned)row * DM + col), o);
;                 }
	s_ashr_i32 s6, s12, 12
	s_mulk_i32 s6, 0x2400
	s_ashr_i32 s7, s6, 31
	s_lshl_b64 s[6:7], s[6:7], 2
	v_readlane_b32 s8, v255, 13
	s_add_u32 s6, s8, s6
	v_readlane_b32 s8, v255, 15
	s_addc_u32 s7, s8, s7
	s_add_u32 s8, s6, 0x1000
	s_addc_u32 s9, s7, 0
	v_lshl_add_u64 v[30:31], s[8:9], 0, v[32:33]
	global_load_dwordx4 v[204:207], v[72:73], off
	v_lshlrev_b32_e32 v176, 2, v70
	v_mov_b32_e32 v177, v33
	v_lshl_add_u64 v[178:179], s[8:9], 0, v[176:177]
	global_load_dwordx4 v[208:211], v[178:179], off
	v_lshl_add_u64 v[180:181], s[6:7], 0, v[176:177]
	global_load_dwordx4 v[212:215], v[180:181], off
	global_load_dwordx4 v[216:219], v[76:77], off
	v_lshlrev_b32_e32 v176, 2, v74
	v_mov_b32_e32 v177, v33
	v_lshl_add_u64 v[178:179], s[8:9], 0, v[176:177]
	global_load_dwordx4 v[220:223], v[178:179], off
	v_lshl_add_u64 v[180:181], s[6:7], 0, v[176:177]
	global_load_dwordx4 v[224:227], v[180:181], off
	global_load_dwordx4 v[228:231], v[80:81], off
	v_lshlrev_b32_e32 v176, 2, v78
	v_mov_b32_e32 v177, v33
	v_lshl_add_u64 v[178:179], s[8:9], 0, v[176:177]
	global_load_dwordx4 v[232:235], v[178:179], off
	v_lshl_add_u64 v[180:181], s[6:7], 0, v[176:177]
	global_load_dwordx4 v[236:239], v[180:181], off
	global_load_dwordx4 v[240:243], v[84:85], off
	v_lshlrev_b32_e32 v176, 2, v82
	v_mov_b32_e32 v177, v33
	v_lshl_add_u64 v[178:179], s[8:9], 0, v[176:177]
	global_load_dwordx4 v[244:247], v[178:179], off
	v_lshl_add_u64 v[180:181], s[6:7], 0, v[176:177]
	global_load_dwordx4 v[248:251], v[180:181], off
	v_lshl_add_u64 v[30:31], s[6:7], 0, v[32:33]
	v_mov_b32_e32 v102, v9
	v_mov_b32_e32 v103, v13
	v_mov_b32_e32 v30, v8
	v_mov_b32_e32 v31, v12
	v_pk_mul_f32 v[102:103], v[102:103], v[102:103]
	v_mov_b32_e32 v104, v1
	v_pk_fma_f32 v[30:31], v[30:31], v[30:31], v[102:103]
	v_mov_b32_e32 v102, v10
	v_mov_b32_e32 v103, v14
	v_pk_fma_f32 v[30:31], v[102:103], v[102:103], v[30:31]
	v_mov_b32_e32 v102, v11
	v_mov_b32_e32 v103, v15
	v_mov_b32_e32 v105, v5
	v_pk_fma_f32 v[30:31], v[102:103], v[102:103], v[30:31]
	v_mov_b32_e32 v102, v0
	v_mov_b32_e32 v103, v4
	v_pk_mul_f32 v[104:105], v[104:105], v[104:105]
	v_add_f32_e32 v29, v30, v31
	v_pk_fma_f32 v[102:103], v[102:103], v[102:103], v[104:105]
	v_mov_b32_e32 v104, v2
	v_mov_b32_e32 v105, v6
	v_pk_fma_f32 v[102:103], v[104:105], v[104:105], v[102:103]
	v_mov_b32_e32 v104, v3
	v_mov_b32_e32 v105, v7
	v_pk_fma_f32 v[102:103], v[104:105], v[104:105], v[102:103]
	s_add_i32 s20, s13, s3
	v_add_f32_e32 v29, v103, v29
	v_add_f32_e32 v29, v102, v29
	ds_bpermute_b32 v30, v71, v29
	s_lshl_b64 s[10:11], s[20:21], 1
	s_mov_b32 s20, 0x800000
	s_add_u32 s10, s84, s10
	s_addc_u32 s11, s85, s11
	s_waitcnt lgkmcnt(0)
	v_add_f32_e32 v29, v29, v30
	ds_bpermute_b32 v30, v75, v29
	s_waitcnt lgkmcnt(0)
	v_add_f32_e32 v29, v29, v30
	ds_bpermute_b32 v30, v79, v29
	s_waitcnt lgkmcnt(0)
	v_add_f32_e32 v29, v29, v30
	ds_bpermute_b32 v30, v83, v29
	s_waitcnt lgkmcnt(0)
	v_add_f32_e32 v29, v29, v30
	ds_bpermute_b32 v30, v87, v29
	s_waitcnt lgkmcnt(0)
	v_add_f32_e32 v29, v29, v30
	ds_bpermute_b32 v30, v88, v29
	s_waitcnt lgkmcnt(0)
	v_add_f32_e32 v29, v29, v30
	v_fmamk_f32 v29, v29, 0x3a800000, v193
	v_mul_f32_e32 v30, 0x4b800000, v29
	v_cmp_gt_f32_e32 vcc, s20, v29
	s_nop 1
	v_cndmask_b32_e32 v29, v29, v30, vcc
	v_rsq_f32_e32 v29, v29
	v_lshl_add_u64 v[30:31], s[8:9], 0, v[62:63]
	v_mul_f32_e32 v32, 0x45800000, v29
	v_cndmask_b32_e32 v32, v29, v32, vcc
	v_pk_mul_f32 v[12:13], v[12:13], v[32:33] op_sel_hi:[1,0]
	v_pk_mul_f32 v[14:15], v[14:15], v[32:33] op_sel_hi:[1,0]
	s_waitcnt vmcnt(9)
	v_mov_b64_e32 v[90:91], v[204:205]
	v_mov_b64_e32 v[92:93], v[206:207]
	v_mov_b64_e32 v[94:95], v[208:209]
	v_mov_b64_e32 v[96:97], v[210:211]
	v_mov_b64_e32 v[98:99], v[212:213]
	v_mov_b64_e32 v[100:101], v[214:215]
	v_pk_mul_f32 v[12:13], v[90:91], v[12:13]
	v_pk_mul_f32 v[14:15], v[92:93], v[14:15]
	v_pk_add_f32 v[90:91], v[94:95], 1.0 op_sel_hi:[1,0]
	v_pk_add_f32 v[92:93], v[96:97], 1.0 op_sel_hi:[1,0]
	v_pk_fma_f32 v[12:13], v[90:91], v[12:13], v[98:99]
	v_pk_fma_f32 v[14:15], v[92:93], v[14:15], v[100:101]
	v_cvt_pk_f16_f32 v12, v12, v13
	v_cvt_pk_f16_f32 v13, v14, v15
	global_store_dwordx2 v64, v[12:13], s[10:11]
	s_nop 0
	v_lshl_add_u64 v[30:31], s[6:7], 0, v[62:63]
	v_pk_mul_f32 v[8:9], v[8:9], v[32:33] op_sel_hi:[1,0]
	v_pk_mul_f32 v[10:11], v[10:11], v[32:33] op_sel_hi:[1,0]
	v_lshl_add_u64 v[30:31], s[8:9], 0, v[58:59]
	v_pk_mul_f32 v[4:5], v[4:5], v[32:33] op_sel_hi:[1,0]
	v_pk_mul_f32 v[6:7], v[6:7], v[32:33] op_sel_hi:[1,0]
	v_pk_mul_f32 v[0:1], v[0:1], v[32:33] op_sel_hi:[1,0]
	v_pk_mul_f32 v[2:3], v[2:3], v[32:33] op_sel_hi:[1,0]
	s_waitcnt vmcnt(7)
	v_mov_b64_e32 v[12:13], v[216:217]
	v_mov_b64_e32 v[14:15], v[218:219]
	v_mov_b64_e32 v[90:91], v[220:221]
	v_mov_b64_e32 v[92:93], v[222:223]
	v_mov_b64_e32 v[62:63], v[224:225]
	v_mov_b64_e32 v[64:65], v[226:227]
	v_pk_mul_f32 v[8:9], v[12:13], v[8:9]
	s_waitcnt lgkmcnt(0)
	v_pk_add_f32 v[12:13], v[90:91], 1.0 op_sel_hi:[1,0]
	v_pk_mul_f32 v[10:11], v[14:15], v[10:11]
	v_pk_add_f32 v[14:15], v[92:93], 1.0 op_sel_hi:[1,0]
	v_pk_fma_f32 v[8:9], v[12:13], v[8:9], v[62:63]
	v_pk_fma_f32 v[10:11], v[14:15], v[10:11], v[64:65]
	v_cvt_pk_f16_f32 v8, v8, v9
	v_cvt_pk_f16_f32 v9, v10, v11
	global_store_dwordx2 v60, v[8:9], s[10:11]
	s_nop 0
	v_lshl_add_u64 v[30:31], s[6:7], 0, v[58:59]
	v_lshl_add_u64 v[30:31], s[8:9], 0, v[54:55]
	s_waitcnt vmcnt(5)
	v_mov_b64_e32 v[8:9], v[228:229]
	v_mov_b64_e32 v[10:11], v[230:231]
	v_mov_b64_e32 v[12:13], v[232:233]
	v_mov_b64_e32 v[14:15], v[234:235]
	v_mov_b64_e32 v[58:59], v[236:237]
	v_mov_b64_e32 v[60:61], v[238:239]
	v_pk_mul_f32 v[4:5], v[8:9], v[4:5]
	s_waitcnt lgkmcnt(0)
	v_pk_add_f32 v[8:9], v[12:13], 1.0 op_sel_hi:[1,0]
	v_pk_mul_f32 v[6:7], v[10:11], v[6:7]
	v_pk_add_f32 v[10:11], v[14:15], 1.0 op_sel_hi:[1,0]
	v_pk_fma_f32 v[4:5], v[4:5], v[8:9], v[58:59]
	v_pk_fma_f32 v[6:7], v[6:7], v[10:11], v[60:61]
	v_cvt_pk_f16_f32 v4, v4, v5
	v_cvt_pk_f16_f32 v5, v6, v7
	global_store_dwordx2 v56, v[4:5], s[10:11]
	s_nop 0
	v_lshl_add_u64 v[12:13], s[6:7], 0, v[54:55]
	s_waitcnt vmcnt(3)
	v_mov_b64_e32 v[4:5], v[240:241]
	v_mov_b64_e32 v[6:7], v[242:243]
	v_mov_b64_e32 v[8:9], v[244:245]
	v_mov_b64_e32 v[10:11], v[246:247]
	v_mov_b64_e32 v[12:13], v[248:249]
	v_mov_b64_e32 v[14:15], v[250:251]
	v_pk_mul_f32 v[0:1], v[0:1], v[4:5]
	s_waitcnt lgkmcnt(0)
	v_pk_add_f32 v[4:5], v[8:9], 1.0 op_sel_hi:[1,0]
	v_pk_mul_f32 v[2:3], v[2:3], v[6:7]
	v_pk_add_f32 v[6:7], v[10:11], 1.0 op_sel_hi:[1,0]
	v_pk_fma_f32 v[0:1], v[0:1], v[4:5], v[12:13]
	v_pk_fma_f32 v[2:3], v[2:3], v[6:7], v[14:15]
	v_cvt_pk_f16_f32 v0, v0, v1
	v_cvt_pk_f16_f32 v1, v2, v3
	global_store_dwordx2 v28, v[0:1], s[10:11]
	s_branch .LBB0_775
